# R2/R3 fast bodies: prefetched iterations skip the row-A index / validity / pointer arithmetic at the head (reuse what the previous middle computed)
# baseline (speedup 1.0000x reference)
;     __device__ __forceinline__ void init(int N, int G, int c, int latent_only) { lat = latent_only; b.init(latent_only ? NB * SEQ : M, N, G, c); }
;     __device__ __forceinline__ void init(int c_, unsigned* cnt_) { lat.init(NB * SEQ, FF2, 1, 0); c = c_; cnt = cnt_; }
; __device__ __forceinline__ void row_pass(const RowPass& R, int gw, int ngw, int lane) {
;     ...
;     for (int row0 = gw; row0 < M; row0 += NR * ngw) {
;         f32x4 v[NR][4]; u32x2 yw[NR][4]; bool act[NR]; float* xrow[NR]; int bbs[NR];
; #pragma unroll
;         for (int k = 0; k < NR; ++k) {
;             const int row = row0 + k * ngw;
;             const int rowc = row < M ? row : row0;
;             const int b = rowc / RPB, i = rowc - b * RPB; const bool isctx = i < CTXL;
;             act[k] = (row < M) && !(isctx && R.skip_ctx);
;             bbs[k] = isctx ? 8 : b;
;             xrow[k] = isctx ? R.xc + ((size_t)b * CTXL + i) * DM : R.out + ((size_t)b * SEQ + (i - CTXL)) * DM;
;             const float* src = R.init ? (isctx ? R.ctx_in + ((size_t)b * CTXL + i) * DM : R.x_in + ((size_t)b * SEQ + (i - CTXL)) * DM) : xrow[k];
.LBB0_132:
	s_cmp_lg_u32 s99, 0
	s_cbranch_scc0 .Lr2_slow_cold
	s_add_i32 s8, s44, s13
	s_mul_hi_i32 s9, s8, 0x78787879
	s_lshr_b32 s25, s9, 31
	s_ashr_i32 s9, s9, 11
	s_add_i32 s9, s9, s25
	s_mul_i32 s25, s9, 0xffffef00
	s_add_i32 s25, s8, s25
	s_cmpk_gt_i32 s25, 0xff
	s_cselect_b64 s[52:53], -1, 0
	s_branch .Lr2_slow_pfa

;     __device__ __forceinline__ void init(int N, int G, int c, int latent_only) { lat = latent_only; b.init(latent_only ? NB * SEQ : M, N, G, c); }
;     __device__ __forceinline__ void init(int c_, unsigned* cnt_) { lat.init(NB * SEQ, FF2, 1, 0); c = c_; cnt = cnt_; }
; __device__ __forceinline__ void row_pass(const RowPass& R, int gw, int ngw, int lane) {
;     ...
;     for (int row0 = gw; row0 < M; row0 += NR * ngw) {
;         f32x4 v[NR][4]; u32x2 yw[NR][4]; bool act[NR]; float* xrow[NR]; int bbs[NR];
; #pragma unroll
;         for (int k = 0; k < NR; ++k) {
;             const int row = row0 + k * ngw;
;             const int rowc = row < M ? row : row0;
;             const int b = rowc / RPB, i = rowc - b * RPB; const bool isctx = i < CTXL;
;             act[k] = (row < M) && !(isctx && R.skip_ctx);
;             bbs[k] = isctx ? 8 : b;
;             xrow[k] = isctx ? R.xc + ((size_t)b * CTXL + i) * DM : R.out + ((size_t)b * SEQ + (i - CTXL)) * DM;
;             const float* src = R.init ? (isctx ? R.ctx_in + ((size_t)b * CTXL + i) * DM : R.x_in + ((size_t)b * SEQ + (i - CTXL)) * DM) : xrow[k];
.LBB0_149:
	s_cmp_lg_u32 s99, 0
	s_cbranch_scc0 .Lr3_slow_cold
	s_add_i32 s8, s44, s19
	s_mul_hi_i32 s9, s8, 0x78787879
	s_lshr_b32 s25, s9, 31
	s_ashr_i32 s9, s9, 11
	s_add_i32 s9, s9, s25
	s_mul_i32 s25, s9, 0xffffef00
	s_add_i32 s25, s8, s25
	s_cmpk_gt_i32 s25, 0xff
	s_cselect_b64 s[52:53], -1, 0
	s_branch .Lr3_slow_pfa
